# E16: E12 + GEMM K-loop MFMAs in snake order (one operand changes per MFMA, same accumulation order)
# baseline (speedup 1.0000x reference)
.LBB0_184:
	s_add_u32 s24, s28, 0xfffc0080
	s_addc_u32 s25, s29, -1
	s_add_i32 s67, 0, 0x10000
	s_cmp_eq_u32 s66, 12
	s_cselect_b32 s41, s57, s25
	s_cselect_b32 s40, s62, s24
	s_cselect_b32 s25, s55, s65
	s_cselect_b32 s24, s63, s64
	s_add_i32 s72, 0, 0x14000
	v_add_u32_e32 v144, s67, v159
	v_add_u32_e32 v180, s72, v159
	ds_read_b128 v[132:135], v144
	ds_read_b128 v[136:139], v144 offset:1024
	ds_read_b128 v[140:143], v144 offset:2048
	ds_read_b128 v[144:147], v144 offset:3072
	ds_read_b128 v[148:151], v180
	ds_read_b128 v[152:155], v180 offset:1024
	ds_read_b128 v[172:175], v180 offset:2048
	ds_read_b128 v[180:183], v180 offset:3072
	v_lshl_add_u64 v[252:253], s[28:29], 0, v[168:169]
	s_add_i32 m0, s84, 0xc000
	ds_read_b128 v[184:187], v246
	ds_read_b128 v[188:191], v246 offset:1024
	ds_read_b128 v[192:195], v246 offset:2048
	ds_read_b128 v[196:199], v246 offset:3072
	ds_read_b128 v[248:251], v246 offset:4096
	ds_read_b128 v[206:209], v246 offset:5120
	ds_read_b128 v[210:213], v246 offset:6144
	ds_read_b128 v[214:217], v246 offset:7168
	global_load_lds_dwordx4 v[252:253], off
	v_lshl_add_u64 v[252:253], s[28:29], 0, v[170:171]
	s_add_i32 m0, s84, 0xe000
	s_nop 0
	global_load_lds_dwordx4 v[252:253], off
	s_waitcnt vmcnt(8)
	s_waitcnt lgkmcnt(0)
	s_barrier
	s_setprio 1
	s_waitcnt lgkmcnt(0)
	v_mfma_f32_16x16x32_bf16 v[128:131], v[132:135], v[184:187], v[128:131]
	v_mfma_f32_16x16x32_bf16 v[112:115], v[132:135], v[192:195], v[112:115]
	v_mfma_f32_16x16x32_bf16 v[96:99], v[132:135], v[248:251], v[96:99]
	v_mfma_f32_16x16x32_bf16 v[80:83], v[132:135], v[210:213], v[80:83]
	v_mfma_f32_16x16x32_bf16 v[76:79], v[140:143], v[210:213], v[76:79]
	v_mfma_f32_16x16x32_bf16 v[92:95], v[140:143], v[248:251], v[92:95]
	v_mfma_f32_16x16x32_bf16 v[108:111], v[140:143], v[192:195], v[108:111]
	v_mfma_f32_16x16x32_bf16 v[124:127], v[140:143], v[184:187], v[124:127]
	v_mfma_f32_16x16x32_bf16 v[128:131], v[136:139], v[188:191], v[128:131]
	v_mfma_f32_16x16x32_bf16 v[112:115], v[136:139], v[196:199], v[112:115]
	v_mfma_f32_16x16x32_bf16 v[96:99], v[136:139], v[206:209], v[96:99]
	v_mfma_f32_16x16x32_bf16 v[80:83], v[136:139], v[214:217], v[80:83]
	v_mfma_f32_16x16x32_bf16 v[76:79], v[144:147], v[214:217], v[76:79]
	v_mfma_f32_16x16x32_bf16 v[92:95], v[144:147], v[206:209], v[92:95]
	v_mfma_f32_16x16x32_bf16 v[108:111], v[144:147], v[196:199], v[108:111]
	v_mfma_f32_16x16x32_bf16 v[124:127], v[144:147], v[188:191], v[124:127]
	s_setprio 0
	s_setprio 1
	v_mfma_f32_16x16x32_bf16 v[120:123], v[148:151], v[184:187], v[120:123]
	v_mfma_f32_16x16x32_bf16 v[104:107], v[148:151], v[192:195], v[104:107]
	v_mfma_f32_16x16x32_bf16 v[88:91], v[148:151], v[248:251], v[88:91]
	v_mfma_f32_16x16x32_bf16 v[72:75], v[148:151], v[210:213], v[72:75]
	v_mfma_f32_16x16x32_bf16 v[68:71], v[172:175], v[210:213], v[68:71]
	v_mfma_f32_16x16x32_bf16 v[84:87], v[172:175], v[248:251], v[84:87]
	v_mfma_f32_16x16x32_bf16 v[100:103], v[172:175], v[192:195], v[100:103]
	v_mfma_f32_16x16x32_bf16 v[116:119], v[172:175], v[184:187], v[116:119]
	v_mfma_f32_16x16x32_bf16 v[120:123], v[152:155], v[188:191], v[120:123]
	v_mfma_f32_16x16x32_bf16 v[104:107], v[152:155], v[196:199], v[104:107]
	v_mfma_f32_16x16x32_bf16 v[88:91], v[152:155], v[206:209], v[88:91]
	v_mfma_f32_16x16x32_bf16 v[72:75], v[152:155], v[214:217], v[72:75]
	v_mfma_f32_16x16x32_bf16 v[68:71], v[180:183], v[214:217], v[68:71]
	v_mfma_f32_16x16x32_bf16 v[84:87], v[180:183], v[206:209], v[84:87]
	v_mfma_f32_16x16x32_bf16 v[100:103], v[180:183], v[196:199], v[100:103]
	v_mfma_f32_16x16x32_bf16 v[116:119], v[180:183], v[188:191], v[116:119]
	s_setprio 0
	s_barrier
	s_add_i32 s67, s67, s3
	v_lshl_add_u64 v[252:253], s[24:25], 0, v[156:157]
	s_mov_b32 m0, s67
	ds_read_b128 v[184:187], v246 offset:16384
	ds_read_b128 v[188:191], v246 offset:17408
	ds_read_b128 v[192:195], v246 offset:18432
	ds_read_b128 v[196:199], v246 offset:19456
	ds_read_b128 v[206:209], v246 offset:20480
	ds_read_b128 v[210:213], v246 offset:21504
	ds_read_b128 v[214:217], v246 offset:22528
	ds_read_b128 v[248:251], v246 offset:23552
	global_load_lds_dwordx4 v[252:253], off
	s_add_i32 m0, s67, 0x2000
	s_add_u32 s96, s24, 0x40000
	v_lshl_add_u64 v[218:219], s[24:25], 0, v[0:1]
	s_addc_u32 s97, s25, 0
	s_add_i32 s67, s72, s3
	global_load_lds_dwordx4 v[218:219], off
	v_lshl_add_u64 v[220:221], s[96:97], 0, v[156:157]
	s_mov_b32 m0, s67
	v_lshl_add_u64 v[222:223], s[40:41], 0, v[0:1]
	global_load_lds_dwordx4 v[220:221], off
	v_lshl_add_u64 v[220:221], s[96:97], 0, v[0:1]
	s_add_i32 m0, s67, 0x2000
	s_nop 0
	global_load_lds_dwordx4 v[220:221], off
	v_lshl_add_u64 v[220:221], s[40:41], 0, v[156:157]
	s_mov_b32 m0, s84
	s_nop 0
	global_load_lds_dwordx4 v[220:221], off
	s_mov_b32 m0, s85
	s_nop 0
	global_load_lds_dwordx4 v[222:223], off
	s_waitcnt vmcnt(8)
	s_waitcnt lgkmcnt(0)
	s_barrier
	s_setprio 1
	s_waitcnt lgkmcnt(0)
	v_mfma_f32_16x16x32_bf16 v[64:67], v[132:135], v[184:187], v[64:67]
	v_mfma_f32_16x16x32_bf16 v[48:51], v[132:135], v[192:195], v[48:51]
	v_mfma_f32_16x16x32_bf16 v[32:35], v[132:135], v[206:209], v[32:35]
	v_mfma_f32_16x16x32_bf16 v[16:19], v[132:135], v[214:217], v[16:19]
	v_mfma_f32_16x16x32_bf16 v[12:15], v[140:143], v[214:217], v[12:15]
	v_mfma_f32_16x16x32_bf16 v[28:31], v[140:143], v[206:209], v[28:31]
	v_mfma_f32_16x16x32_bf16 v[44:47], v[140:143], v[192:195], v[44:47]
	v_mfma_f32_16x16x32_bf16 v[60:63], v[140:143], v[184:187], v[60:63]
	v_mfma_f32_16x16x32_bf16 v[64:67], v[136:139], v[188:191], v[64:67]
	v_mfma_f32_16x16x32_bf16 v[48:51], v[136:139], v[196:199], v[48:51]
	v_mfma_f32_16x16x32_bf16 v[32:35], v[136:139], v[210:213], v[32:35]
	v_mfma_f32_16x16x32_bf16 v[16:19], v[136:139], v[248:251], v[16:19]
	v_mfma_f32_16x16x32_bf16 v[12:15], v[144:147], v[248:251], v[12:15]
	v_mfma_f32_16x16x32_bf16 v[28:31], v[144:147], v[210:213], v[28:31]
	v_mfma_f32_16x16x32_bf16 v[44:47], v[144:147], v[196:199], v[44:47]
	v_mfma_f32_16x16x32_bf16 v[60:63], v[144:147], v[188:191], v[60:63]
	s_setprio 0
	s_setprio 1
	v_mfma_f32_16x16x32_bf16 v[56:59], v[148:151], v[184:187], v[56:59]
	v_mfma_f32_16x16x32_bf16 v[40:43], v[148:151], v[192:195], v[40:43]
	v_mfma_f32_16x16x32_bf16 v[24:27], v[148:151], v[206:209], v[24:27]
	v_mfma_f32_16x16x32_bf16 v[8:11], v[148:151], v[214:217], v[8:11]
	v_mfma_f32_16x16x32_bf16 v[4:7], v[172:175], v[214:217], v[4:7]
	v_mfma_f32_16x16x32_bf16 v[20:23], v[172:175], v[206:209], v[20:23]
	v_mfma_f32_16x16x32_bf16 v[36:39], v[172:175], v[192:195], v[36:39]
	v_mfma_f32_16x16x32_bf16 v[52:55], v[172:175], v[184:187], v[52:55]
	v_mfma_f32_16x16x32_bf16 v[56:59], v[152:155], v[188:191], v[56:59]
	v_mfma_f32_16x16x32_bf16 v[40:43], v[152:155], v[196:199], v[40:43]
	v_mfma_f32_16x16x32_bf16 v[24:27], v[152:155], v[210:213], v[24:27]
	v_mfma_f32_16x16x32_bf16 v[8:11], v[152:155], v[248:251], v[8:11]
	v_mfma_f32_16x16x32_bf16 v[4:7], v[180:183], v[248:251], v[4:7]
	v_mfma_f32_16x16x32_bf16 v[20:23], v[180:183], v[210:213], v[20:23]
	v_mfma_f32_16x16x32_bf16 v[36:39], v[180:183], v[196:199], v[36:39]
	v_mfma_f32_16x16x32_bf16 v[52:55], v[180:183], v[188:191], v[52:55]
	s_setprio 0
	s_barrier
	s_add_i32 s67, 0, 0x18000
	s_add_i32 s72, 0, 0x1c000
	v_add_u32_e32 v144, s67, v159
	v_add_u32_e32 v180, s72, v159
	ds_read_b128 v[132:135], v144
	ds_read_b128 v[136:139], v144 offset:1024
	ds_read_b128 v[140:143], v144 offset:2048
	ds_read_b128 v[144:147], v144 offset:3072
	ds_read_b128 v[148:151], v180
	ds_read_b128 v[152:155], v180 offset:1024
	ds_read_b128 v[172:175], v180 offset:2048
	ds_read_b128 v[180:183], v180 offset:3072
	s_add_u32 s40, s40, 0x40000
	s_addc_u32 s41, s41, 0
	s_mov_b32 m0, s86
	v_lshl_add_u64 v[224:225], s[40:41], 0, v[156:157]
	ds_read_b128 v[184:187], v246 offset:32768
	ds_read_b128 v[188:191], v246 offset:33792
	ds_read_b128 v[192:195], v246 offset:34816
	ds_read_b128 v[196:199], v246 offset:35840
	ds_read_b128 v[206:209], v246 offset:36864
	ds_read_b128 v[210:213], v246 offset:37888
	ds_read_b128 v[214:217], v246 offset:38912
	ds_read_b128 v[248:251], v246 offset:39936
	global_load_lds_dwordx4 v[224:225], off
	v_lshl_add_u64 v[224:225], s[40:41], 0, v[0:1]
	s_mov_b32 m0, s87
	s_nop 0
	global_load_lds_dwordx4 v[224:225], off
	s_waitcnt vmcnt(8)
	s_waitcnt lgkmcnt(0)
	s_barrier
	s_setprio 1
	s_waitcnt lgkmcnt(0)
	v_mfma_f32_16x16x32_bf16 v[128:131], v[132:135], v[184:187], v[128:131]
	v_mfma_f32_16x16x32_bf16 v[112:115], v[132:135], v[192:195], v[112:115]
	v_mfma_f32_16x16x32_bf16 v[96:99], v[132:135], v[206:209], v[96:99]
	v_mfma_f32_16x16x32_bf16 v[80:83], v[132:135], v[214:217], v[80:83]
	v_mfma_f32_16x16x32_bf16 v[76:79], v[140:143], v[214:217], v[76:79]
	v_mfma_f32_16x16x32_bf16 v[92:95], v[140:143], v[206:209], v[92:95]
	v_mfma_f32_16x16x32_bf16 v[108:111], v[140:143], v[192:195], v[108:111]
	v_mfma_f32_16x16x32_bf16 v[124:127], v[140:143], v[184:187], v[124:127]
	v_mfma_f32_16x16x32_bf16 v[128:131], v[136:139], v[188:191], v[128:131]
	v_mfma_f32_16x16x32_bf16 v[112:115], v[136:139], v[196:199], v[112:115]
	v_mfma_f32_16x16x32_bf16 v[96:99], v[136:139], v[210:213], v[96:99]
	v_mfma_f32_16x16x32_bf16 v[80:83], v[136:139], v[248:251], v[80:83]
	v_mfma_f32_16x16x32_bf16 v[76:79], v[144:147], v[248:251], v[76:79]
	v_mfma_f32_16x16x32_bf16 v[92:95], v[144:147], v[210:213], v[92:95]
	v_mfma_f32_16x16x32_bf16 v[108:111], v[144:147], v[196:199], v[108:111]
	v_mfma_f32_16x16x32_bf16 v[124:127], v[144:147], v[188:191], v[124:127]
	s_setprio 0
	s_setprio 1
	v_mfma_f32_16x16x32_bf16 v[120:123], v[148:151], v[184:187], v[120:123]
	v_mfma_f32_16x16x32_bf16 v[104:107], v[148:151], v[192:195], v[104:107]
	v_mfma_f32_16x16x32_bf16 v[88:91], v[148:151], v[206:209], v[88:91]
	v_mfma_f32_16x16x32_bf16 v[72:75], v[148:151], v[214:217], v[72:75]
	v_mfma_f32_16x16x32_bf16 v[68:71], v[172:175], v[214:217], v[68:71]
	v_mfma_f32_16x16x32_bf16 v[84:87], v[172:175], v[206:209], v[84:87]
	v_mfma_f32_16x16x32_bf16 v[100:103], v[172:175], v[192:195], v[100:103]
	v_mfma_f32_16x16x32_bf16 v[116:119], v[172:175], v[184:187], v[116:119]
	v_mfma_f32_16x16x32_bf16 v[120:123], v[152:155], v[188:191], v[120:123]
	v_mfma_f32_16x16x32_bf16 v[104:107], v[152:155], v[196:199], v[104:107]
	v_mfma_f32_16x16x32_bf16 v[88:91], v[152:155], v[210:213], v[88:91]
	v_mfma_f32_16x16x32_bf16 v[72:75], v[152:155], v[248:251], v[72:75]
	v_mfma_f32_16x16x32_bf16 v[68:71], v[180:183], v[248:251], v[68:71]
	v_mfma_f32_16x16x32_bf16 v[84:87], v[180:183], v[210:213], v[84:87]
	v_mfma_f32_16x16x32_bf16 v[100:103], v[180:183], v[196:199], v[100:103]
	v_mfma_f32_16x16x32_bf16 v[116:119], v[180:183], v[188:191], v[116:119]
	s_setprio 0
	s_barrier
	s_add_i32 s40, s67, s3
	v_lshl_add_u64 v[224:225], v[252:253], 0, s[30:31]
	s_mov_b32 m0, s40
	ds_read_b128 v[184:187], v246 offset:49152
	ds_read_b128 v[188:191], v246 offset:50176
	ds_read_b128 v[192:195], v246 offset:51200
	ds_read_b128 v[196:199], v246 offset:52224
	ds_read_b128 v[206:209], v246 offset:53248
	ds_read_b128 v[210:213], v246 offset:54272
	ds_read_b128 v[214:217], v246 offset:55296
	ds_read_b128 v[248:251], v246 offset:56320
	global_load_lds_dwordx4 v[224:225], off
	s_add_i32 m0, s40, 0x2000
	s_add_u32 s24, s24, 0x40080
	v_lshl_add_u64 v[218:219], v[218:219], 0, s[30:31]
	s_addc_u32 s25, s25, 0
	s_add_i32 s40, s72, s3
	global_load_lds_dwordx4 v[218:219], off
	v_lshl_add_u64 v[218:219], s[24:25], 0, v[156:157]
	s_mov_b32 m0, s40
	s_nop 0
	global_load_lds_dwordx4 v[218:219], off
	v_lshl_add_u64 v[218:219], s[24:25], 0, v[0:1]
	s_add_i32 m0, s40, 0x2000
	s_nop 0
	global_load_lds_dwordx4 v[218:219], off
	v_lshl_add_u64 v[218:219], v[220:221], 0, s[30:31]
	s_mov_b32 m0, s92
	s_nop 0
	global_load_lds_dwordx4 v[218:219], off
	v_lshl_add_u64 v[218:219], v[222:223], 0, s[30:31]
	s_mov_b32 m0, s93
	s_nop 0
	global_load_lds_dwordx4 v[218:219], off
	s_waitcnt vmcnt(8)
	s_waitcnt lgkmcnt(0)
	s_barrier
	s_setprio 1
	s_waitcnt lgkmcnt(0)
	v_mfma_f32_16x16x32_bf16 v[64:67], v[132:135], v[184:187], v[64:67]
	v_mfma_f32_16x16x32_bf16 v[48:51], v[132:135], v[192:195], v[48:51]
	v_mfma_f32_16x16x32_bf16 v[32:35], v[132:135], v[206:209], v[32:35]
	v_mfma_f32_16x16x32_bf16 v[16:19], v[132:135], v[214:217], v[16:19]
	v_mfma_f32_16x16x32_bf16 v[12:15], v[140:143], v[214:217], v[12:15]
	v_mfma_f32_16x16x32_bf16 v[28:31], v[140:143], v[206:209], v[28:31]
	v_mfma_f32_16x16x32_bf16 v[44:47], v[140:143], v[192:195], v[44:47]
	v_mfma_f32_16x16x32_bf16 v[60:63], v[140:143], v[184:187], v[60:63]
	v_mfma_f32_16x16x32_bf16 v[64:67], v[136:139], v[188:191], v[64:67]
	v_mfma_f32_16x16x32_bf16 v[48:51], v[136:139], v[196:199], v[48:51]
	v_mfma_f32_16x16x32_bf16 v[32:35], v[136:139], v[210:213], v[32:35]
	v_mfma_f32_16x16x32_bf16 v[16:19], v[136:139], v[248:251], v[16:19]
	v_mfma_f32_16x16x32_bf16 v[12:15], v[144:147], v[248:251], v[12:15]
	v_mfma_f32_16x16x32_bf16 v[28:31], v[144:147], v[210:213], v[28:31]
	v_mfma_f32_16x16x32_bf16 v[44:47], v[144:147], v[196:199], v[44:47]
	v_mfma_f32_16x16x32_bf16 v[60:63], v[144:147], v[188:191], v[60:63]
	s_setprio 0
	s_setprio 1
	v_mfma_f32_16x16x32_bf16 v[56:59], v[148:151], v[184:187], v[56:59]
	v_mfma_f32_16x16x32_bf16 v[40:43], v[148:151], v[192:195], v[40:43]
	v_mfma_f32_16x16x32_bf16 v[24:27], v[148:151], v[206:209], v[24:27]
	v_mfma_f32_16x16x32_bf16 v[8:11], v[148:151], v[214:217], v[8:11]
	v_mfma_f32_16x16x32_bf16 v[4:7], v[172:175], v[214:217], v[4:7]
	v_mfma_f32_16x16x32_bf16 v[20:23], v[172:175], v[206:209], v[20:23]
	v_mfma_f32_16x16x32_bf16 v[36:39], v[172:175], v[192:195], v[36:39]
	v_mfma_f32_16x16x32_bf16 v[52:55], v[172:175], v[184:187], v[52:55]
	v_mfma_f32_16x16x32_bf16 v[56:59], v[152:155], v[188:191], v[56:59]
	v_mfma_f32_16x16x32_bf16 v[40:43], v[152:155], v[196:199], v[40:43]
	v_mfma_f32_16x16x32_bf16 v[24:27], v[152:155], v[210:213], v[24:27]
	v_mfma_f32_16x16x32_bf16 v[8:11], v[152:155], v[248:251], v[8:11]
	v_mfma_f32_16x16x32_bf16 v[4:7], v[180:183], v[248:251], v[4:7]
	v_mfma_f32_16x16x32_bf16 v[20:23], v[180:183], v[210:213], v[20:23]
	v_mfma_f32_16x16x32_bf16 v[36:39], v[180:183], v[196:199], v[36:39]
	v_mfma_f32_16x16x32_bf16 v[52:55], v[180:183], v[188:191], v[52:55]
	s_setprio 0
	s_barrier
	s_add_i32 s66, s66, 2
	s_add_u32 s28, s28, 0x100
	s_addc_u32 s29, s29, 0
	s_add_u32 s64, s64, 0x100
	s_addc_u32 s65, s65, 0
	s_cmp_gt_u32 s66, 13
	s_cbranch_scc0 .LBB0_184
	s_and_b64 vcc, exec, s[52:53]
	s_cbranch_vccz .LBB0_187
	s_barrier

.LBB0_800:
	s_add_u32 s64, s62, 0x100
	s_addc_u32 s65, s63, 0
	s_add_i32 s72, 0, 0x10000
	s_cmp_eq_u32 s96, 12
	s_cselect_b32 s67, s57, s65
	s_cselect_b32 s66, s92, s64
	v_add_u32_e32 v145, s72, v142
	s_cselect_b32 s25, s55, s95
	s_cselect_b32 s24, s93, s94
	s_add_i32 s73, 0, 0x14000
	ds_read_b128 v[138:141], v145
	ds_read_b128 v[146:149], v145 offset:1024
	ds_read_b128 v[150:153], v145 offset:2048
	ds_read_b128 v[154:157], v145 offset:3072
	v_add_u32_e32 v145, s73, v142
	ds_read_b128 v[158:161], v145
	ds_read_b128 v[162:165], v145 offset:1024
	ds_read_b128 v[166:169], v145 offset:2048
	ds_read_b128 v[170:173], v145 offset:3072
	v_lshl_add_u64 v[174:175], s[62:63], 0, v[134:135]
	s_add_i32 m0, s84, 0xc000
	ds_read_b128 v[180:183], v144
	ds_read_b128 v[184:187], v144 offset:1024
	ds_read_b128 v[188:191], v144 offset:2048
	ds_read_b128 v[192:195], v144 offset:3072
	ds_read_b128 v[196:199], v144 offset:4096
	ds_read_b128 v[206:209], v144 offset:5120
	ds_read_b128 v[210:213], v144 offset:6144
	ds_read_b128 v[214:217], v144 offset:7168
	global_load_lds_dwordx4 v[174:175], off
	v_lshl_add_u64 v[174:175], s[62:63], 0, v[136:137]
	s_add_i32 m0, s84, 0xe000
	s_nop 0
	global_load_lds_dwordx4 v[174:175], off
	s_waitcnt vmcnt(8)
	s_waitcnt lgkmcnt(0)
	s_barrier
	s_setprio 1
	s_waitcnt lgkmcnt(0)
	v_mfma_f32_16x16x32_bf16 v[128:131], v[138:141], v[180:183], v[128:131]
	v_mfma_f32_16x16x32_bf16 v[112:115], v[138:141], v[188:191], v[112:115]
	v_mfma_f32_16x16x32_bf16 v[96:99], v[138:141], v[196:199], v[96:99]
	v_mfma_f32_16x16x32_bf16 v[80:83], v[138:141], v[210:213], v[80:83]
	v_mfma_f32_16x16x32_bf16 v[76:79], v[150:153], v[210:213], v[76:79]
	v_mfma_f32_16x16x32_bf16 v[92:95], v[150:153], v[196:199], v[92:95]
	v_mfma_f32_16x16x32_bf16 v[108:111], v[150:153], v[188:191], v[108:111]
	v_mfma_f32_16x16x32_bf16 v[124:127], v[150:153], v[180:183], v[124:127]
	v_mfma_f32_16x16x32_bf16 v[128:131], v[146:149], v[184:187], v[128:131]
	v_mfma_f32_16x16x32_bf16 v[112:115], v[146:149], v[192:195], v[112:115]
	v_mfma_f32_16x16x32_bf16 v[96:99], v[146:149], v[206:209], v[96:99]
	v_mfma_f32_16x16x32_bf16 v[80:83], v[146:149], v[214:217], v[80:83]
	v_mfma_f32_16x16x32_bf16 v[76:79], v[154:157], v[214:217], v[76:79]
	v_mfma_f32_16x16x32_bf16 v[92:95], v[154:157], v[206:209], v[92:95]
	v_mfma_f32_16x16x32_bf16 v[108:111], v[154:157], v[192:195], v[108:111]
	v_mfma_f32_16x16x32_bf16 v[124:127], v[154:157], v[184:187], v[124:127]
	s_setprio 0
	s_setprio 1
	v_mfma_f32_16x16x32_bf16 v[120:123], v[158:161], v[180:183], v[120:123]
	v_mfma_f32_16x16x32_bf16 v[104:107], v[158:161], v[188:191], v[104:107]
	v_mfma_f32_16x16x32_bf16 v[88:91], v[158:161], v[196:199], v[88:91]
	v_mfma_f32_16x16x32_bf16 v[72:75], v[158:161], v[210:213], v[72:75]
	v_mfma_f32_16x16x32_bf16 v[68:71], v[166:169], v[210:213], v[68:71]
	v_mfma_f32_16x16x32_bf16 v[84:87], v[166:169], v[196:199], v[84:87]
	v_mfma_f32_16x16x32_bf16 v[100:103], v[166:169], v[188:191], v[100:103]
	v_mfma_f32_16x16x32_bf16 v[116:119], v[166:169], v[180:183], v[116:119]
	v_mfma_f32_16x16x32_bf16 v[120:123], v[162:165], v[184:187], v[120:123]
	v_mfma_f32_16x16x32_bf16 v[104:107], v[162:165], v[192:195], v[104:107]
	v_mfma_f32_16x16x32_bf16 v[88:91], v[162:165], v[206:209], v[88:91]
	v_mfma_f32_16x16x32_bf16 v[72:75], v[162:165], v[214:217], v[72:75]
	v_mfma_f32_16x16x32_bf16 v[68:71], v[170:173], v[214:217], v[68:71]
	v_mfma_f32_16x16x32_bf16 v[84:87], v[170:173], v[206:209], v[84:87]
	v_mfma_f32_16x16x32_bf16 v[100:103], v[170:173], v[192:195], v[100:103]
	v_mfma_f32_16x16x32_bf16 v[116:119], v[170:173], v[184:187], v[116:119]
	s_setprio 0
	s_barrier
	s_add_i32 s62, s72, s71
	v_lshl_add_u64 v[174:175], s[24:25], 0, v[132:133]
	s_mov_b32 m0, s62
	ds_read_b128 v[180:183], v144 offset:16384
	ds_read_b128 v[184:187], v144 offset:17408
	ds_read_b128 v[188:191], v144 offset:18432
	ds_read_b128 v[192:195], v144 offset:19456
	ds_read_b128 v[196:199], v144 offset:20480
	ds_read_b128 v[206:209], v144 offset:21504
	ds_read_b128 v[210:213], v144 offset:22528
	ds_read_b128 v[214:217], v144 offset:23552
	global_load_lds_dwordx4 v[174:175], off
	s_add_i32 m0, s62, 0x2000
	s_add_u32 s62, s24, 0x40000
	v_lshl_add_u64 v[218:219], s[24:25], 0, v[0:1]
	s_addc_u32 s63, s25, 0
	s_add_i32 s72, s73, s71
	global_load_lds_dwordx4 v[218:219], off
	v_lshl_add_u64 v[220:221], s[62:63], 0, v[132:133]
	s_mov_b32 m0, s72
	v_lshl_add_u64 v[222:223], s[66:67], 0, v[0:1]
	global_load_lds_dwordx4 v[220:221], off
	v_lshl_add_u64 v[220:221], s[62:63], 0, v[0:1]
	s_add_i32 m0, s72, 0x2000
	s_nop 0
	global_load_lds_dwordx4 v[220:221], off
	v_lshl_add_u64 v[220:221], s[66:67], 0, v[132:133]
	s_mov_b32 m0, s84
	s_nop 0
	global_load_lds_dwordx4 v[220:221], off
	s_mov_b32 m0, s85
	s_nop 0
	global_load_lds_dwordx4 v[222:223], off
	s_waitcnt vmcnt(8)
	s_waitcnt lgkmcnt(0)
	s_barrier
	s_setprio 1
	s_waitcnt lgkmcnt(0)
	v_mfma_f32_16x16x32_bf16 v[64:67], v[138:141], v[180:183], v[64:67]
	v_mfma_f32_16x16x32_bf16 v[48:51], v[138:141], v[188:191], v[48:51]
	v_mfma_f32_16x16x32_bf16 v[32:35], v[138:141], v[196:199], v[32:35]
	v_mfma_f32_16x16x32_bf16 v[16:19], v[138:141], v[210:213], v[16:19]
	v_mfma_f32_16x16x32_bf16 v[12:15], v[150:153], v[210:213], v[12:15]
	v_mfma_f32_16x16x32_bf16 v[28:31], v[150:153], v[196:199], v[28:31]
	v_mfma_f32_16x16x32_bf16 v[44:47], v[150:153], v[188:191], v[44:47]
	v_mfma_f32_16x16x32_bf16 v[60:63], v[150:153], v[180:183], v[60:63]
	v_mfma_f32_16x16x32_bf16 v[64:67], v[146:149], v[184:187], v[64:67]
	v_mfma_f32_16x16x32_bf16 v[48:51], v[146:149], v[192:195], v[48:51]
	v_mfma_f32_16x16x32_bf16 v[32:35], v[146:149], v[206:209], v[32:35]
	v_mfma_f32_16x16x32_bf16 v[16:19], v[146:149], v[214:217], v[16:19]
	v_mfma_f32_16x16x32_bf16 v[12:15], v[154:157], v[214:217], v[12:15]
	v_mfma_f32_16x16x32_bf16 v[28:31], v[154:157], v[206:209], v[28:31]
	v_mfma_f32_16x16x32_bf16 v[44:47], v[154:157], v[192:195], v[44:47]
	v_mfma_f32_16x16x32_bf16 v[60:63], v[154:157], v[184:187], v[60:63]
	s_setprio 0
	s_setprio 1
	v_mfma_f32_16x16x32_bf16 v[56:59], v[158:161], v[180:183], v[56:59]
	v_mfma_f32_16x16x32_bf16 v[40:43], v[158:161], v[188:191], v[40:43]
	v_mfma_f32_16x16x32_bf16 v[24:27], v[158:161], v[196:199], v[24:27]
	v_mfma_f32_16x16x32_bf16 v[8:11], v[158:161], v[210:213], v[8:11]
	v_mfma_f32_16x16x32_bf16 v[4:7], v[166:169], v[210:213], v[4:7]
	v_mfma_f32_16x16x32_bf16 v[20:23], v[166:169], v[196:199], v[20:23]
	v_mfma_f32_16x16x32_bf16 v[36:39], v[166:169], v[188:191], v[36:39]
	v_mfma_f32_16x16x32_bf16 v[52:55], v[166:169], v[180:183], v[52:55]
	v_mfma_f32_16x16x32_bf16 v[56:59], v[162:165], v[184:187], v[56:59]
	v_mfma_f32_16x16x32_bf16 v[40:43], v[162:165], v[192:195], v[40:43]
	v_mfma_f32_16x16x32_bf16 v[24:27], v[162:165], v[206:209], v[24:27]
	v_mfma_f32_16x16x32_bf16 v[8:11], v[162:165], v[214:217], v[8:11]
	v_mfma_f32_16x16x32_bf16 v[4:7], v[170:173], v[214:217], v[4:7]
	v_mfma_f32_16x16x32_bf16 v[20:23], v[170:173], v[206:209], v[20:23]
	v_mfma_f32_16x16x32_bf16 v[36:39], v[170:173], v[192:195], v[36:39]
	v_mfma_f32_16x16x32_bf16 v[52:55], v[170:173], v[184:187], v[52:55]
	s_setprio 0
	s_barrier
	s_add_i32 s72, 0, 0x18000
	v_add_u32_e32 v145, s72, v142
	s_add_i32 s73, 0, 0x1c000
	ds_read_b128 v[138:141], v145
	ds_read_b128 v[146:149], v145 offset:1024
	ds_read_b128 v[150:153], v145 offset:2048
	ds_read_b128 v[154:157], v145 offset:3072
	v_add_u32_e32 v145, s73, v142
	ds_read_b128 v[158:161], v145
	ds_read_b128 v[162:165], v145 offset:1024
	ds_read_b128 v[166:169], v145 offset:2048
	ds_read_b128 v[170:173], v145 offset:3072
	s_add_u32 s62, s66, 0x40000
	s_addc_u32 s63, s67, 0
	s_mov_b32 m0, s86
	v_lshl_add_u64 v[224:225], s[62:63], 0, v[132:133]
	ds_read_b128 v[180:183], v144 offset:32768
	ds_read_b128 v[184:187], v144 offset:33792
	ds_read_b128 v[188:191], v144 offset:34816
	ds_read_b128 v[192:195], v144 offset:35840
	ds_read_b128 v[196:199], v144 offset:36864
	ds_read_b128 v[206:209], v144 offset:37888
	ds_read_b128 v[210:213], v144 offset:38912
	ds_read_b128 v[214:217], v144 offset:39936
	global_load_lds_dwordx4 v[224:225], off
	v_lshl_add_u64 v[224:225], s[62:63], 0, v[0:1]
	s_mov_b32 m0, s87
	s_nop 0
	global_load_lds_dwordx4 v[224:225], off
	s_waitcnt vmcnt(8)
	s_waitcnt lgkmcnt(0)
	s_barrier
	s_setprio 1
	s_waitcnt lgkmcnt(0)
	v_mfma_f32_16x16x32_bf16 v[128:131], v[138:141], v[180:183], v[128:131]
	v_mfma_f32_16x16x32_bf16 v[112:115], v[138:141], v[188:191], v[112:115]
	v_mfma_f32_16x16x32_bf16 v[96:99], v[138:141], v[196:199], v[96:99]
	v_mfma_f32_16x16x32_bf16 v[80:83], v[138:141], v[210:213], v[80:83]
	v_mfma_f32_16x16x32_bf16 v[76:79], v[150:153], v[210:213], v[76:79]
	v_mfma_f32_16x16x32_bf16 v[92:95], v[150:153], v[196:199], v[92:95]
	v_mfma_f32_16x16x32_bf16 v[108:111], v[150:153], v[188:191], v[108:111]
	v_mfma_f32_16x16x32_bf16 v[124:127], v[150:153], v[180:183], v[124:127]
	v_mfma_f32_16x16x32_bf16 v[128:131], v[146:149], v[184:187], v[128:131]
	v_mfma_f32_16x16x32_bf16 v[112:115], v[146:149], v[192:195], v[112:115]
	v_mfma_f32_16x16x32_bf16 v[96:99], v[146:149], v[206:209], v[96:99]
	v_mfma_f32_16x16x32_bf16 v[80:83], v[146:149], v[214:217], v[80:83]
	v_mfma_f32_16x16x32_bf16 v[76:79], v[154:157], v[214:217], v[76:79]
	v_mfma_f32_16x16x32_bf16 v[92:95], v[154:157], v[206:209], v[92:95]
	v_mfma_f32_16x16x32_bf16 v[108:111], v[154:157], v[192:195], v[108:111]
	v_mfma_f32_16x16x32_bf16 v[124:127], v[154:157], v[184:187], v[124:127]
	s_setprio 0
	s_setprio 1
	v_mfma_f32_16x16x32_bf16 v[120:123], v[158:161], v[180:183], v[120:123]
	v_mfma_f32_16x16x32_bf16 v[104:107], v[158:161], v[188:191], v[104:107]
	v_mfma_f32_16x16x32_bf16 v[88:91], v[158:161], v[196:199], v[88:91]
	v_mfma_f32_16x16x32_bf16 v[72:75], v[158:161], v[210:213], v[72:75]
	v_mfma_f32_16x16x32_bf16 v[68:71], v[166:169], v[210:213], v[68:71]
	v_mfma_f32_16x16x32_bf16 v[84:87], v[166:169], v[196:199], v[84:87]
	v_mfma_f32_16x16x32_bf16 v[100:103], v[166:169], v[188:191], v[100:103]
	v_mfma_f32_16x16x32_bf16 v[116:119], v[166:169], v[180:183], v[116:119]
	v_mfma_f32_16x16x32_bf16 v[120:123], v[162:165], v[184:187], v[120:123]
	v_mfma_f32_16x16x32_bf16 v[104:107], v[162:165], v[192:195], v[104:107]
	v_mfma_f32_16x16x32_bf16 v[88:91], v[162:165], v[206:209], v[88:91]
	v_mfma_f32_16x16x32_bf16 v[72:75], v[162:165], v[214:217], v[72:75]
	v_mfma_f32_16x16x32_bf16 v[68:71], v[170:173], v[214:217], v[68:71]
	v_mfma_f32_16x16x32_bf16 v[84:87], v[170:173], v[206:209], v[84:87]
	v_mfma_f32_16x16x32_bf16 v[100:103], v[170:173], v[192:195], v[100:103]
	v_mfma_f32_16x16x32_bf16 v[116:119], v[170:173], v[184:187], v[116:119]
	s_setprio 0
	s_barrier
	s_add_i32 s62, s72, s71
	v_lshl_add_u64 v[174:175], v[174:175], 0, s[30:31]
	s_mov_b32 m0, s62
	ds_read_b128 v[180:183], v144 offset:49152
	ds_read_b128 v[184:187], v144 offset:50176
	ds_read_b128 v[188:191], v144 offset:51200
	ds_read_b128 v[192:195], v144 offset:52224
	ds_read_b128 v[196:199], v144 offset:53248
	ds_read_b128 v[206:209], v144 offset:54272
	ds_read_b128 v[210:213], v144 offset:55296
	ds_read_b128 v[214:217], v144 offset:56320
	global_load_lds_dwordx4 v[174:175], off
	s_add_i32 m0, s62, 0x2000
	s_add_u32 s24, s24, 0x40080
	v_lshl_add_u64 v[174:175], v[218:219], 0, s[30:31]
	s_addc_u32 s25, s25, 0
	s_add_i32 s62, s73, s71
	global_load_lds_dwordx4 v[174:175], off
	v_lshl_add_u64 v[174:175], s[24:25], 0, v[132:133]
	s_mov_b32 m0, s62
	s_nop 0
	global_load_lds_dwordx4 v[174:175], off
	v_lshl_add_u64 v[174:175], s[24:25], 0, v[0:1]
	s_add_i32 m0, s62, 0x2000
	s_nop 0
	global_load_lds_dwordx4 v[174:175], off
	v_lshl_add_u64 v[174:175], v[220:221], 0, s[30:31]
	s_mov_b32 m0, s26
	s_nop 0
	global_load_lds_dwordx4 v[174:175], off
	v_lshl_add_u64 v[174:175], v[222:223], 0, s[30:31]
	s_mov_b32 m0, s88
	s_nop 0
	global_load_lds_dwordx4 v[174:175], off
	s_waitcnt vmcnt(8)
	s_waitcnt lgkmcnt(0)
	s_barrier
	s_setprio 1
	s_waitcnt lgkmcnt(0)
	v_mfma_f32_16x16x32_bf16 v[64:67], v[138:141], v[180:183], v[64:67]
	v_mfma_f32_16x16x32_bf16 v[48:51], v[138:141], v[188:191], v[48:51]
	v_mfma_f32_16x16x32_bf16 v[32:35], v[138:141], v[196:199], v[32:35]
	v_mfma_f32_16x16x32_bf16 v[16:19], v[138:141], v[210:213], v[16:19]
	v_mfma_f32_16x16x32_bf16 v[12:15], v[150:153], v[210:213], v[12:15]
	v_mfma_f32_16x16x32_bf16 v[28:31], v[150:153], v[196:199], v[28:31]
	v_mfma_f32_16x16x32_bf16 v[44:47], v[150:153], v[188:191], v[44:47]
	v_mfma_f32_16x16x32_bf16 v[60:63], v[150:153], v[180:183], v[60:63]
	v_mfma_f32_16x16x32_bf16 v[64:67], v[146:149], v[184:187], v[64:67]
	v_mfma_f32_16x16x32_bf16 v[48:51], v[146:149], v[192:195], v[48:51]
	v_mfma_f32_16x16x32_bf16 v[32:35], v[146:149], v[206:209], v[32:35]
	v_mfma_f32_16x16x32_bf16 v[16:19], v[146:149], v[214:217], v[16:19]
	v_mfma_f32_16x16x32_bf16 v[12:15], v[154:157], v[214:217], v[12:15]
	v_mfma_f32_16x16x32_bf16 v[28:31], v[154:157], v[206:209], v[28:31]
	v_mfma_f32_16x16x32_bf16 v[44:47], v[154:157], v[192:195], v[44:47]
	v_mfma_f32_16x16x32_bf16 v[60:63], v[154:157], v[184:187], v[60:63]
	s_setprio 0
	s_setprio 1
	v_mfma_f32_16x16x32_bf16 v[56:59], v[158:161], v[180:183], v[56:59]
	v_mfma_f32_16x16x32_bf16 v[40:43], v[158:161], v[188:191], v[40:43]
	v_mfma_f32_16x16x32_bf16 v[24:27], v[158:161], v[196:199], v[24:27]
	v_mfma_f32_16x16x32_bf16 v[8:11], v[158:161], v[210:213], v[8:11]
	v_mfma_f32_16x16x32_bf16 v[4:7], v[166:169], v[210:213], v[4:7]
	v_mfma_f32_16x16x32_bf16 v[20:23], v[166:169], v[196:199], v[20:23]
	v_mfma_f32_16x16x32_bf16 v[36:39], v[166:169], v[188:191], v[36:39]
	v_mfma_f32_16x16x32_bf16 v[52:55], v[166:169], v[180:183], v[52:55]
	v_mfma_f32_16x16x32_bf16 v[56:59], v[162:165], v[184:187], v[56:59]
	v_mfma_f32_16x16x32_bf16 v[40:43], v[162:165], v[192:195], v[40:43]
	v_mfma_f32_16x16x32_bf16 v[24:27], v[162:165], v[206:209], v[24:27]
	v_mfma_f32_16x16x32_bf16 v[8:11], v[162:165], v[214:217], v[8:11]
	v_mfma_f32_16x16x32_bf16 v[4:7], v[170:173], v[214:217], v[4:7]
	v_mfma_f32_16x16x32_bf16 v[20:23], v[170:173], v[206:209], v[20:23]
	v_mfma_f32_16x16x32_bf16 v[36:39], v[170:173], v[192:195], v[36:39]
	v_mfma_f32_16x16x32_bf16 v[52:55], v[170:173], v[184:187], v[52:55]
	s_setprio 0
	s_barrier
	s_add_i32 s96, s96, 2
	s_add_u32 s94, s94, 0x100
	s_addc_u32 s95, s95, 0
	s_cmp_gt_u32 s96, 13
	s_mov_b64 s[62:63], s[64:65]
	s_cbranch_scc0 .LBB0_800
	s_and_b64 vcc, exec, s[52:53]
	s_cbranch_vccz .LBB0_803
	s_barrier

.LBB0_889:
	s_add_u32 s24, s28, 0xfffc0080
	s_addc_u32 s25, s29, -1
	s_add_i32 s72, 0, 0x10000
	s_cmp_eq_u32 s88, 12
	s_cselect_b32 s59, s53, s25
	s_cselect_b32 s58, s84, s24
	v_add_u32_e32 v149, s72, v146
	s_cselect_b32 s25, s51, s87
	s_cselect_b32 s24, s85, s86
	s_add_i32 s89, 0, 0x14000
	ds_read_b128 v[138:141], v149
	ds_read_b128 v[142:145], v149 offset:1024
	ds_read_b128 v[150:153], v149 offset:2048
	ds_read_b128 v[154:157], v149 offset:3072
	v_add_u32_e32 v149, s89, v146
	ds_read_b128 v[158:161], v149
	ds_read_b128 v[162:165], v149 offset:1024
	ds_read_b128 v[166:169], v149 offset:2048
	ds_read_b128 v[170:173], v149 offset:3072
	v_lshl_add_u64 v[174:175], s[28:29], 0, v[134:135]
	s_add_i32 m0, s64, 0xc000
	ds_read_b128 v[180:183], v148
	ds_read_b128 v[184:187], v148 offset:1024
	ds_read_b128 v[188:191], v148 offset:2048
	ds_read_b128 v[192:195], v148 offset:3072
	ds_read_b128 v[196:199], v148 offset:4096
	ds_read_b128 v[206:209], v148 offset:5120
	ds_read_b128 v[210:213], v148 offset:6144
	ds_read_b128 v[214:217], v148 offset:7168
	global_load_lds_dwordx4 v[174:175], off
	v_lshl_add_u64 v[174:175], s[28:29], 0, v[136:137]
	s_add_i32 m0, s64, 0xe000
	s_nop 0
	global_load_lds_dwordx4 v[174:175], off
	s_waitcnt vmcnt(8)
	s_waitcnt lgkmcnt(0)
	s_barrier
	s_setprio 1
	s_waitcnt lgkmcnt(0)
	v_mfma_f32_16x16x32_bf16 v[128:131], v[138:141], v[180:183], v[128:131]
	v_mfma_f32_16x16x32_bf16 v[112:115], v[138:141], v[188:191], v[112:115]
	v_mfma_f32_16x16x32_bf16 v[96:99], v[138:141], v[196:199], v[96:99]
	v_mfma_f32_16x16x32_bf16 v[80:83], v[138:141], v[210:213], v[80:83]
	v_mfma_f32_16x16x32_bf16 v[76:79], v[150:153], v[210:213], v[76:79]
	v_mfma_f32_16x16x32_bf16 v[92:95], v[150:153], v[196:199], v[92:95]
	v_mfma_f32_16x16x32_bf16 v[108:111], v[150:153], v[188:191], v[108:111]
	v_mfma_f32_16x16x32_bf16 v[124:127], v[150:153], v[180:183], v[124:127]
	v_mfma_f32_16x16x32_bf16 v[128:131], v[142:145], v[184:187], v[128:131]
	v_mfma_f32_16x16x32_bf16 v[112:115], v[142:145], v[192:195], v[112:115]
	v_mfma_f32_16x16x32_bf16 v[96:99], v[142:145], v[206:209], v[96:99]
	v_mfma_f32_16x16x32_bf16 v[80:83], v[142:145], v[214:217], v[80:83]
	v_mfma_f32_16x16x32_bf16 v[76:79], v[154:157], v[214:217], v[76:79]
	v_mfma_f32_16x16x32_bf16 v[92:95], v[154:157], v[206:209], v[92:95]
	v_mfma_f32_16x16x32_bf16 v[108:111], v[154:157], v[192:195], v[108:111]
	v_mfma_f32_16x16x32_bf16 v[124:127], v[154:157], v[184:187], v[124:127]
	s_setprio 0
	s_setprio 1
	v_mfma_f32_16x16x32_bf16 v[120:123], v[158:161], v[180:183], v[120:123]
	v_mfma_f32_16x16x32_bf16 v[104:107], v[158:161], v[188:191], v[104:107]
	v_mfma_f32_16x16x32_bf16 v[88:91], v[158:161], v[196:199], v[88:91]
	v_mfma_f32_16x16x32_bf16 v[72:75], v[158:161], v[210:213], v[72:75]
	v_mfma_f32_16x16x32_bf16 v[68:71], v[166:169], v[210:213], v[68:71]
	v_mfma_f32_16x16x32_bf16 v[84:87], v[166:169], v[196:199], v[84:87]
	v_mfma_f32_16x16x32_bf16 v[100:103], v[166:169], v[188:191], v[100:103]
	v_mfma_f32_16x16x32_bf16 v[116:119], v[166:169], v[180:183], v[116:119]
	v_mfma_f32_16x16x32_bf16 v[120:123], v[162:165], v[184:187], v[120:123]
	v_mfma_f32_16x16x32_bf16 v[104:107], v[162:165], v[192:195], v[104:107]
	v_mfma_f32_16x16x32_bf16 v[88:91], v[162:165], v[206:209], v[88:91]
	v_mfma_f32_16x16x32_bf16 v[72:75], v[162:165], v[214:217], v[72:75]
	v_mfma_f32_16x16x32_bf16 v[68:71], v[170:173], v[214:217], v[68:71]
	v_mfma_f32_16x16x32_bf16 v[84:87], v[170:173], v[206:209], v[84:87]
	v_mfma_f32_16x16x32_bf16 v[100:103], v[170:173], v[192:195], v[100:103]
	v_mfma_f32_16x16x32_bf16 v[116:119], v[170:173], v[184:187], v[116:119]
	s_setprio 0
	s_barrier
	s_add_i32 s72, s72, s63
	v_lshl_add_u64 v[174:175], s[24:25], 0, v[132:133]
	s_mov_b32 m0, s72
	ds_read_b128 v[180:183], v148 offset:16384
	ds_read_b128 v[184:187], v148 offset:17408
	ds_read_b128 v[188:191], v148 offset:18432
	ds_read_b128 v[192:195], v148 offset:19456
	ds_read_b128 v[196:199], v148 offset:20480
	ds_read_b128 v[206:209], v148 offset:21504
	ds_read_b128 v[210:213], v148 offset:22528
	ds_read_b128 v[214:217], v148 offset:23552
	global_load_lds_dwordx4 v[174:175], off
	s_add_i32 m0, s72, 0x2000
	s_add_u32 s72, s24, 0x40000
	v_lshl_add_u64 v[218:219], s[24:25], 0, v[0:1]
	s_addc_u32 s73, s25, 0
	s_add_i32 s89, s89, s63
	global_load_lds_dwordx4 v[218:219], off
	v_lshl_add_u64 v[220:221], s[72:73], 0, v[132:133]
	s_mov_b32 m0, s89
	v_lshl_add_u64 v[222:223], s[58:59], 0, v[0:1]
	global_load_lds_dwordx4 v[220:221], off
	v_lshl_add_u64 v[220:221], s[72:73], 0, v[0:1]
	s_add_i32 m0, s89, 0x2000
	s_nop 0
	global_load_lds_dwordx4 v[220:221], off
	v_lshl_add_u64 v[220:221], s[58:59], 0, v[132:133]
	s_mov_b32 m0, s64
	s_nop 0
	global_load_lds_dwordx4 v[220:221], off
	s_mov_b32 m0, s65
	s_nop 0
	global_load_lds_dwordx4 v[222:223], off
	s_waitcnt vmcnt(8)
	s_waitcnt lgkmcnt(0)
	s_barrier
	s_setprio 1
	s_waitcnt lgkmcnt(0)
	v_mfma_f32_16x16x32_bf16 v[64:67], v[138:141], v[180:183], v[64:67]
	v_mfma_f32_16x16x32_bf16 v[48:51], v[138:141], v[188:191], v[48:51]
	v_mfma_f32_16x16x32_bf16 v[32:35], v[138:141], v[196:199], v[32:35]
	v_mfma_f32_16x16x32_bf16 v[16:19], v[138:141], v[210:213], v[16:19]
	v_mfma_f32_16x16x32_bf16 v[12:15], v[150:153], v[210:213], v[12:15]
	v_mfma_f32_16x16x32_bf16 v[28:31], v[150:153], v[196:199], v[28:31]
	v_mfma_f32_16x16x32_bf16 v[44:47], v[150:153], v[188:191], v[44:47]
	v_mfma_f32_16x16x32_bf16 v[60:63], v[150:153], v[180:183], v[60:63]
	v_mfma_f32_16x16x32_bf16 v[64:67], v[142:145], v[184:187], v[64:67]
	v_mfma_f32_16x16x32_bf16 v[48:51], v[142:145], v[192:195], v[48:51]
	v_mfma_f32_16x16x32_bf16 v[32:35], v[142:145], v[206:209], v[32:35]
	v_mfma_f32_16x16x32_bf16 v[16:19], v[142:145], v[214:217], v[16:19]
	v_mfma_f32_16x16x32_bf16 v[12:15], v[154:157], v[214:217], v[12:15]
	v_mfma_f32_16x16x32_bf16 v[28:31], v[154:157], v[206:209], v[28:31]
	v_mfma_f32_16x16x32_bf16 v[44:47], v[154:157], v[192:195], v[44:47]
	v_mfma_f32_16x16x32_bf16 v[60:63], v[154:157], v[184:187], v[60:63]
	s_setprio 0
	s_setprio 1
	v_mfma_f32_16x16x32_bf16 v[56:59], v[158:161], v[180:183], v[56:59]
	v_mfma_f32_16x16x32_bf16 v[40:43], v[158:161], v[188:191], v[40:43]
	v_mfma_f32_16x16x32_bf16 v[24:27], v[158:161], v[196:199], v[24:27]
	v_mfma_f32_16x16x32_bf16 v[8:11], v[158:161], v[210:213], v[8:11]
	v_mfma_f32_16x16x32_bf16 v[4:7], v[166:169], v[210:213], v[4:7]
	v_mfma_f32_16x16x32_bf16 v[20:23], v[166:169], v[196:199], v[20:23]
	v_mfma_f32_16x16x32_bf16 v[36:39], v[166:169], v[188:191], v[36:39]
	v_mfma_f32_16x16x32_bf16 v[52:55], v[166:169], v[180:183], v[52:55]
	v_mfma_f32_16x16x32_bf16 v[56:59], v[162:165], v[184:187], v[56:59]
	v_mfma_f32_16x16x32_bf16 v[40:43], v[162:165], v[192:195], v[40:43]
	v_mfma_f32_16x16x32_bf16 v[24:27], v[162:165], v[206:209], v[24:27]
	v_mfma_f32_16x16x32_bf16 v[8:11], v[162:165], v[214:217], v[8:11]
	v_mfma_f32_16x16x32_bf16 v[4:7], v[170:173], v[214:217], v[4:7]
	v_mfma_f32_16x16x32_bf16 v[20:23], v[170:173], v[206:209], v[20:23]
	v_mfma_f32_16x16x32_bf16 v[36:39], v[170:173], v[192:195], v[36:39]
	v_mfma_f32_16x16x32_bf16 v[52:55], v[170:173], v[184:187], v[52:55]
	s_setprio 0
	s_barrier
	s_add_i32 s72, 0, 0x18000
	v_add_u32_e32 v149, s72, v146
	s_add_i32 s73, 0, 0x1c000
	ds_read_b128 v[138:141], v149
	ds_read_b128 v[142:145], v149 offset:1024
	ds_read_b128 v[150:153], v149 offset:2048
	ds_read_b128 v[154:157], v149 offset:3072
	v_add_u32_e32 v149, s73, v146
	ds_read_b128 v[158:161], v149
	ds_read_b128 v[162:165], v149 offset:1024
	ds_read_b128 v[166:169], v149 offset:2048
	ds_read_b128 v[170:173], v149 offset:3072
	s_add_u32 s58, s58, 0x40000
	s_addc_u32 s59, s59, 0
	s_mov_b32 m0, s66
	v_lshl_add_u64 v[224:225], s[58:59], 0, v[132:133]
	ds_read_b128 v[180:183], v148 offset:32768
	ds_read_b128 v[184:187], v148 offset:33792
	ds_read_b128 v[188:191], v148 offset:34816
	ds_read_b128 v[192:195], v148 offset:35840
	ds_read_b128 v[196:199], v148 offset:36864
	ds_read_b128 v[206:209], v148 offset:37888
	ds_read_b128 v[210:213], v148 offset:38912
	ds_read_b128 v[214:217], v148 offset:39936
	global_load_lds_dwordx4 v[224:225], off
	v_lshl_add_u64 v[224:225], s[58:59], 0, v[0:1]
	s_mov_b32 m0, s67
	s_nop 0
	global_load_lds_dwordx4 v[224:225], off
	s_waitcnt vmcnt(8)
	s_waitcnt lgkmcnt(0)
	s_barrier
	s_setprio 1
	s_waitcnt lgkmcnt(0)
	v_mfma_f32_16x16x32_bf16 v[128:131], v[138:141], v[180:183], v[128:131]
	v_mfma_f32_16x16x32_bf16 v[112:115], v[138:141], v[188:191], v[112:115]
	v_mfma_f32_16x16x32_bf16 v[96:99], v[138:141], v[196:199], v[96:99]
	v_mfma_f32_16x16x32_bf16 v[80:83], v[138:141], v[210:213], v[80:83]
	v_mfma_f32_16x16x32_bf16 v[76:79], v[150:153], v[210:213], v[76:79]
	v_mfma_f32_16x16x32_bf16 v[92:95], v[150:153], v[196:199], v[92:95]
	v_mfma_f32_16x16x32_bf16 v[108:111], v[150:153], v[188:191], v[108:111]
	v_mfma_f32_16x16x32_bf16 v[124:127], v[150:153], v[180:183], v[124:127]
	v_mfma_f32_16x16x32_bf16 v[128:131], v[142:145], v[184:187], v[128:131]
	v_mfma_f32_16x16x32_bf16 v[112:115], v[142:145], v[192:195], v[112:115]
	v_mfma_f32_16x16x32_bf16 v[96:99], v[142:145], v[206:209], v[96:99]
	v_mfma_f32_16x16x32_bf16 v[80:83], v[142:145], v[214:217], v[80:83]
	v_mfma_f32_16x16x32_bf16 v[76:79], v[154:157], v[214:217], v[76:79]
	v_mfma_f32_16x16x32_bf16 v[92:95], v[154:157], v[206:209], v[92:95]
	v_mfma_f32_16x16x32_bf16 v[108:111], v[154:157], v[192:195], v[108:111]
	v_mfma_f32_16x16x32_bf16 v[124:127], v[154:157], v[184:187], v[124:127]
	s_setprio 0
	s_setprio 1
	v_mfma_f32_16x16x32_bf16 v[120:123], v[158:161], v[180:183], v[120:123]
	v_mfma_f32_16x16x32_bf16 v[104:107], v[158:161], v[188:191], v[104:107]
	v_mfma_f32_16x16x32_bf16 v[88:91], v[158:161], v[196:199], v[88:91]
	v_mfma_f32_16x16x32_bf16 v[72:75], v[158:161], v[210:213], v[72:75]
	v_mfma_f32_16x16x32_bf16 v[68:71], v[166:169], v[210:213], v[68:71]
	v_mfma_f32_16x16x32_bf16 v[84:87], v[166:169], v[196:199], v[84:87]
	v_mfma_f32_16x16x32_bf16 v[100:103], v[166:169], v[188:191], v[100:103]
	v_mfma_f32_16x16x32_bf16 v[116:119], v[166:169], v[180:183], v[116:119]
	v_mfma_f32_16x16x32_bf16 v[120:123], v[162:165], v[184:187], v[120:123]
	v_mfma_f32_16x16x32_bf16 v[104:107], v[162:165], v[192:195], v[104:107]
	v_mfma_f32_16x16x32_bf16 v[88:91], v[162:165], v[206:209], v[88:91]
	v_mfma_f32_16x16x32_bf16 v[72:75], v[162:165], v[214:217], v[72:75]
	v_mfma_f32_16x16x32_bf16 v[68:71], v[170:173], v[214:217], v[68:71]
	v_mfma_f32_16x16x32_bf16 v[84:87], v[170:173], v[206:209], v[84:87]
	v_mfma_f32_16x16x32_bf16 v[100:103], v[170:173], v[192:195], v[100:103]
	v_mfma_f32_16x16x32_bf16 v[116:119], v[170:173], v[184:187], v[116:119]
	s_setprio 0
	s_barrier
	s_add_i32 s58, s72, s63
	v_lshl_add_u64 v[174:175], v[174:175], 0, s[30:31]
	s_mov_b32 m0, s58
	ds_read_b128 v[180:183], v148 offset:49152
	ds_read_b128 v[184:187], v148 offset:50176
	ds_read_b128 v[188:191], v148 offset:51200
	ds_read_b128 v[192:195], v148 offset:52224
	ds_read_b128 v[196:199], v148 offset:53248
	ds_read_b128 v[206:209], v148 offset:54272
	ds_read_b128 v[210:213], v148 offset:55296
	ds_read_b128 v[214:217], v148 offset:56320
	global_load_lds_dwordx4 v[174:175], off
	s_add_i32 m0, s58, 0x2000
	s_add_u32 s24, s24, 0x40080
	v_lshl_add_u64 v[174:175], v[218:219], 0, s[30:31]
	s_addc_u32 s25, s25, 0
	s_add_i32 s58, s73, s63
	global_load_lds_dwordx4 v[174:175], off
	v_lshl_add_u64 v[174:175], s[24:25], 0, v[132:133]
	s_mov_b32 m0, s58
	s_nop 0
	global_load_lds_dwordx4 v[174:175], off
	v_lshl_add_u64 v[174:175], s[24:25], 0, v[0:1]
	s_add_i32 m0, s58, 0x2000
	s_nop 0
	global_load_lds_dwordx4 v[174:175], off
	v_lshl_add_u64 v[174:175], v[220:221], 0, s[30:31]
	s_mov_b32 m0, s26
	s_nop 0
	global_load_lds_dwordx4 v[174:175], off
	v_lshl_add_u64 v[174:175], v[222:223], 0, s[30:31]
	s_mov_b32 m0, s68
	s_nop 0
	global_load_lds_dwordx4 v[174:175], off
	s_waitcnt vmcnt(8)
	s_waitcnt lgkmcnt(0)
	s_barrier
	s_setprio 1
	s_waitcnt lgkmcnt(0)
	v_mfma_f32_16x16x32_bf16 v[64:67], v[138:141], v[180:183], v[64:67]
	v_mfma_f32_16x16x32_bf16 v[48:51], v[138:141], v[188:191], v[48:51]
	v_mfma_f32_16x16x32_bf16 v[32:35], v[138:141], v[196:199], v[32:35]
	v_mfma_f32_16x16x32_bf16 v[16:19], v[138:141], v[210:213], v[16:19]
	v_mfma_f32_16x16x32_bf16 v[12:15], v[150:153], v[210:213], v[12:15]
	v_mfma_f32_16x16x32_bf16 v[28:31], v[150:153], v[196:199], v[28:31]
	v_mfma_f32_16x16x32_bf16 v[44:47], v[150:153], v[188:191], v[44:47]
	v_mfma_f32_16x16x32_bf16 v[60:63], v[150:153], v[180:183], v[60:63]
	v_mfma_f32_16x16x32_bf16 v[64:67], v[142:145], v[184:187], v[64:67]
	v_mfma_f32_16x16x32_bf16 v[48:51], v[142:145], v[192:195], v[48:51]
	v_mfma_f32_16x16x32_bf16 v[32:35], v[142:145], v[206:209], v[32:35]
	v_mfma_f32_16x16x32_bf16 v[16:19], v[142:145], v[214:217], v[16:19]
	v_mfma_f32_16x16x32_bf16 v[12:15], v[154:157], v[214:217], v[12:15]
	v_mfma_f32_16x16x32_bf16 v[28:31], v[154:157], v[206:209], v[28:31]
	v_mfma_f32_16x16x32_bf16 v[44:47], v[154:157], v[192:195], v[44:47]
	v_mfma_f32_16x16x32_bf16 v[60:63], v[154:157], v[184:187], v[60:63]
	s_setprio 0
	s_setprio 1
	v_mfma_f32_16x16x32_bf16 v[56:59], v[158:161], v[180:183], v[56:59]
	v_mfma_f32_16x16x32_bf16 v[40:43], v[158:161], v[188:191], v[40:43]
	v_mfma_f32_16x16x32_bf16 v[24:27], v[158:161], v[196:199], v[24:27]
	v_mfma_f32_16x16x32_bf16 v[8:11], v[158:161], v[210:213], v[8:11]
	v_mfma_f32_16x16x32_bf16 v[4:7], v[166:169], v[210:213], v[4:7]
	v_mfma_f32_16x16x32_bf16 v[20:23], v[166:169], v[196:199], v[20:23]
	v_mfma_f32_16x16x32_bf16 v[36:39], v[166:169], v[188:191], v[36:39]
	v_mfma_f32_16x16x32_bf16 v[52:55], v[166:169], v[180:183], v[52:55]
	v_mfma_f32_16x16x32_bf16 v[56:59], v[162:165], v[184:187], v[56:59]
	v_mfma_f32_16x16x32_bf16 v[40:43], v[162:165], v[192:195], v[40:43]
	v_mfma_f32_16x16x32_bf16 v[24:27], v[162:165], v[206:209], v[24:27]
	v_mfma_f32_16x16x32_bf16 v[8:11], v[162:165], v[214:217], v[8:11]
	v_mfma_f32_16x16x32_bf16 v[4:7], v[170:173], v[214:217], v[4:7]
	v_mfma_f32_16x16x32_bf16 v[20:23], v[170:173], v[206:209], v[20:23]
	v_mfma_f32_16x16x32_bf16 v[36:39], v[170:173], v[192:195], v[36:39]
	v_mfma_f32_16x16x32_bf16 v[52:55], v[170:173], v[184:187], v[52:55]
	s_setprio 0
	s_barrier
	s_add_i32 s88, s88, 2
	s_add_u32 s28, s28, 0x100
	s_addc_u32 s29, s29, 0
	s_add_u32 s86, s86, 0x100
	s_addc_u32 s87, s87, 0
	s_cmp_gt_u32 s88, 13
	s_cbranch_scc0 .LBB0_889
	s_and_b64 vcc, exec, s[48:49]
	s_cbranch_vccz .LBB0_892
	s_barrier

.LBB0_961:
	s_add_u32 s60, s28, 0x100
	s_addc_u32 s61, s29, 0
	s_add_i32 s72, 0, 0x10000
	s_cmp_eq_u32 s92, 60
	s_cselect_b32 s63, s55, s61
	s_cselect_b32 s62, s88, s60
	v_add_u32_e32 v149, s72, v146
	s_cselect_b32 s25, s53, s91
	s_cselect_b32 s24, s89, s90
	s_add_i32 s73, 0, 0x14000
	ds_read_b128 v[138:141], v149
	ds_read_b128 v[142:145], v149 offset:1024
	ds_read_b128 v[150:153], v149 offset:2048
	ds_read_b128 v[154:157], v149 offset:3072
	v_add_u32_e32 v149, s73, v146
	ds_read_b128 v[158:161], v149
	ds_read_b128 v[162:165], v149 offset:1024
	ds_read_b128 v[166:169], v149 offset:2048
	ds_read_b128 v[170:173], v149 offset:3072
	v_lshl_add_u64 v[174:175], s[28:29], 0, v[134:135]
	s_add_i32 m0, s67, 0xc000
	ds_read_b128 v[180:183], v148
	ds_read_b128 v[184:187], v148 offset:1024
	ds_read_b128 v[188:191], v148 offset:2048
	ds_read_b128 v[192:195], v148 offset:3072
	ds_read_b128 v[196:199], v148 offset:4096
	ds_read_b128 v[206:209], v148 offset:5120
	ds_read_b128 v[210:213], v148 offset:6144
	ds_read_b128 v[214:217], v148 offset:7168
	global_load_lds_dwordx4 v[174:175], off
	v_lshl_add_u64 v[174:175], s[28:29], 0, v[136:137]
	s_add_i32 m0, s67, 0xe000
	s_nop 0
	global_load_lds_dwordx4 v[174:175], off
	s_waitcnt vmcnt(8)
	s_waitcnt lgkmcnt(0)
	s_barrier
	s_setprio 1
	s_waitcnt lgkmcnt(0)
	v_mfma_f32_16x16x32_bf16 v[128:131], v[138:141], v[180:183], v[128:131]
	v_mfma_f32_16x16x32_bf16 v[112:115], v[138:141], v[188:191], v[112:115]
	v_mfma_f32_16x16x32_bf16 v[96:99], v[138:141], v[196:199], v[96:99]
	v_mfma_f32_16x16x32_bf16 v[80:83], v[138:141], v[210:213], v[80:83]
	v_mfma_f32_16x16x32_bf16 v[76:79], v[150:153], v[210:213], v[76:79]
	v_mfma_f32_16x16x32_bf16 v[92:95], v[150:153], v[196:199], v[92:95]
	v_mfma_f32_16x16x32_bf16 v[108:111], v[150:153], v[188:191], v[108:111]
	v_mfma_f32_16x16x32_bf16 v[124:127], v[150:153], v[180:183], v[124:127]
	v_mfma_f32_16x16x32_bf16 v[128:131], v[142:145], v[184:187], v[128:131]
	v_mfma_f32_16x16x32_bf16 v[112:115], v[142:145], v[192:195], v[112:115]
	v_mfma_f32_16x16x32_bf16 v[96:99], v[142:145], v[206:209], v[96:99]
	v_mfma_f32_16x16x32_bf16 v[80:83], v[142:145], v[214:217], v[80:83]
	v_mfma_f32_16x16x32_bf16 v[76:79], v[154:157], v[214:217], v[76:79]
	v_mfma_f32_16x16x32_bf16 v[92:95], v[154:157], v[206:209], v[92:95]
	v_mfma_f32_16x16x32_bf16 v[108:111], v[154:157], v[192:195], v[108:111]
	v_mfma_f32_16x16x32_bf16 v[124:127], v[154:157], v[184:187], v[124:127]
	s_setprio 0
	s_setprio 1
	v_mfma_f32_16x16x32_bf16 v[120:123], v[158:161], v[180:183], v[120:123]
	v_mfma_f32_16x16x32_bf16 v[104:107], v[158:161], v[188:191], v[104:107]
	v_mfma_f32_16x16x32_bf16 v[88:91], v[158:161], v[196:199], v[88:91]
	v_mfma_f32_16x16x32_bf16 v[72:75], v[158:161], v[210:213], v[72:75]
	v_mfma_f32_16x16x32_bf16 v[68:71], v[166:169], v[210:213], v[68:71]
	v_mfma_f32_16x16x32_bf16 v[84:87], v[166:169], v[196:199], v[84:87]
	v_mfma_f32_16x16x32_bf16 v[100:103], v[166:169], v[188:191], v[100:103]
	v_mfma_f32_16x16x32_bf16 v[116:119], v[166:169], v[180:183], v[116:119]
	v_mfma_f32_16x16x32_bf16 v[120:123], v[162:165], v[184:187], v[120:123]
	v_mfma_f32_16x16x32_bf16 v[104:107], v[162:165], v[192:195], v[104:107]
	v_mfma_f32_16x16x32_bf16 v[88:91], v[162:165], v[206:209], v[88:91]
	v_mfma_f32_16x16x32_bf16 v[72:75], v[162:165], v[214:217], v[72:75]
	v_mfma_f32_16x16x32_bf16 v[68:71], v[170:173], v[214:217], v[68:71]
	v_mfma_f32_16x16x32_bf16 v[84:87], v[170:173], v[206:209], v[84:87]
	v_mfma_f32_16x16x32_bf16 v[100:103], v[170:173], v[192:195], v[100:103]
	v_mfma_f32_16x16x32_bf16 v[116:119], v[170:173], v[184:187], v[116:119]
	s_setprio 0
	s_barrier
	s_add_i32 s28, s72, s66
	v_lshl_add_u64 v[174:175], s[24:25], 0, v[132:133]
	s_mov_b32 m0, s28
	ds_read_b128 v[180:183], v148 offset:16384
	ds_read_b128 v[184:187], v148 offset:17408
	ds_read_b128 v[188:191], v148 offset:18432
	ds_read_b128 v[192:195], v148 offset:19456
	ds_read_b128 v[196:199], v148 offset:20480
	ds_read_b128 v[206:209], v148 offset:21504
	ds_read_b128 v[210:213], v148 offset:22528
	ds_read_b128 v[214:217], v148 offset:23552
	global_load_lds_dwordx4 v[174:175], off
	s_add_i32 m0, s28, 0x2000
	s_add_u32 s28, s24, 0x100000
	v_lshl_add_u64 v[218:219], s[24:25], 0, v[0:1]
	s_addc_u32 s29, s25, 0
	s_add_i32 s72, s73, s66
	global_load_lds_dwordx4 v[218:219], off
	v_lshl_add_u64 v[220:221], s[28:29], 0, v[132:133]
	s_mov_b32 m0, s72
	v_lshl_add_u64 v[222:223], s[62:63], 0, v[0:1]
	global_load_lds_dwordx4 v[220:221], off
	v_lshl_add_u64 v[220:221], s[28:29], 0, v[0:1]
	s_add_i32 m0, s72, 0x2000
	s_nop 0
	global_load_lds_dwordx4 v[220:221], off
	v_lshl_add_u64 v[220:221], s[62:63], 0, v[132:133]
	s_mov_b32 m0, s67
	s_nop 0
	global_load_lds_dwordx4 v[220:221], off
	s_mov_b32 m0, s68
	s_nop 0
	global_load_lds_dwordx4 v[222:223], off
	s_waitcnt vmcnt(8)
	s_waitcnt lgkmcnt(0)
	s_barrier
	s_setprio 1
	s_waitcnt lgkmcnt(0)
	v_mfma_f32_16x16x32_bf16 v[64:67], v[138:141], v[180:183], v[64:67]
	v_mfma_f32_16x16x32_bf16 v[48:51], v[138:141], v[188:191], v[48:51]
	v_mfma_f32_16x16x32_bf16 v[32:35], v[138:141], v[196:199], v[32:35]
	v_mfma_f32_16x16x32_bf16 v[16:19], v[138:141], v[210:213], v[16:19]
	v_mfma_f32_16x16x32_bf16 v[12:15], v[150:153], v[210:213], v[12:15]
	v_mfma_f32_16x16x32_bf16 v[28:31], v[150:153], v[196:199], v[28:31]
	v_mfma_f32_16x16x32_bf16 v[44:47], v[150:153], v[188:191], v[44:47]
	v_mfma_f32_16x16x32_bf16 v[60:63], v[150:153], v[180:183], v[60:63]
	v_mfma_f32_16x16x32_bf16 v[64:67], v[142:145], v[184:187], v[64:67]
	v_mfma_f32_16x16x32_bf16 v[48:51], v[142:145], v[192:195], v[48:51]
	v_mfma_f32_16x16x32_bf16 v[32:35], v[142:145], v[206:209], v[32:35]
	v_mfma_f32_16x16x32_bf16 v[16:19], v[142:145], v[214:217], v[16:19]
	v_mfma_f32_16x16x32_bf16 v[12:15], v[154:157], v[214:217], v[12:15]
	v_mfma_f32_16x16x32_bf16 v[28:31], v[154:157], v[206:209], v[28:31]
	v_mfma_f32_16x16x32_bf16 v[44:47], v[154:157], v[192:195], v[44:47]
	v_mfma_f32_16x16x32_bf16 v[60:63], v[154:157], v[184:187], v[60:63]
	s_setprio 0
	s_setprio 1
	v_mfma_f32_16x16x32_bf16 v[56:59], v[158:161], v[180:183], v[56:59]
	v_mfma_f32_16x16x32_bf16 v[40:43], v[158:161], v[188:191], v[40:43]
	v_mfma_f32_16x16x32_bf16 v[24:27], v[158:161], v[196:199], v[24:27]
	v_mfma_f32_16x16x32_bf16 v[8:11], v[158:161], v[210:213], v[8:11]
	v_mfma_f32_16x16x32_bf16 v[4:7], v[166:169], v[210:213], v[4:7]
	v_mfma_f32_16x16x32_bf16 v[20:23], v[166:169], v[196:199], v[20:23]
	v_mfma_f32_16x16x32_bf16 v[36:39], v[166:169], v[188:191], v[36:39]
	v_mfma_f32_16x16x32_bf16 v[52:55], v[166:169], v[180:183], v[52:55]
	v_mfma_f32_16x16x32_bf16 v[56:59], v[162:165], v[184:187], v[56:59]
	v_mfma_f32_16x16x32_bf16 v[40:43], v[162:165], v[192:195], v[40:43]
	v_mfma_f32_16x16x32_bf16 v[24:27], v[162:165], v[206:209], v[24:27]
	v_mfma_f32_16x16x32_bf16 v[8:11], v[162:165], v[214:217], v[8:11]
	v_mfma_f32_16x16x32_bf16 v[4:7], v[170:173], v[214:217], v[4:7]
	v_mfma_f32_16x16x32_bf16 v[20:23], v[170:173], v[206:209], v[20:23]
	v_mfma_f32_16x16x32_bf16 v[36:39], v[170:173], v[192:195], v[36:39]
	v_mfma_f32_16x16x32_bf16 v[52:55], v[170:173], v[184:187], v[52:55]
	s_setprio 0
	s_barrier
	s_add_i32 s72, 0, 0x18000
	v_add_u32_e32 v149, s72, v146
	s_add_i32 s73, 0, 0x1c000
	ds_read_b128 v[138:141], v149
	ds_read_b128 v[142:145], v149 offset:1024
	ds_read_b128 v[150:153], v149 offset:2048
	ds_read_b128 v[154:157], v149 offset:3072
	v_add_u32_e32 v149, s73, v146
	ds_read_b128 v[158:161], v149
	ds_read_b128 v[162:165], v149 offset:1024
	ds_read_b128 v[166:169], v149 offset:2048
	ds_read_b128 v[170:173], v149 offset:3072
	s_add_u32 s28, s62, 0x100000
	s_addc_u32 s29, s63, 0
	s_mov_b32 m0, s69
	v_lshl_add_u64 v[224:225], s[28:29], 0, v[132:133]
	ds_read_b128 v[180:183], v148 offset:32768
	ds_read_b128 v[184:187], v148 offset:33792
	ds_read_b128 v[188:191], v148 offset:34816
	ds_read_b128 v[192:195], v148 offset:35840
	ds_read_b128 v[196:199], v148 offset:36864
	ds_read_b128 v[206:209], v148 offset:37888
	ds_read_b128 v[210:213], v148 offset:38912
	ds_read_b128 v[214:217], v148 offset:39936
	global_load_lds_dwordx4 v[224:225], off
	v_lshl_add_u64 v[224:225], s[28:29], 0, v[0:1]
	s_mov_b32 m0, s70
	s_nop 0
	global_load_lds_dwordx4 v[224:225], off
	s_waitcnt vmcnt(8)
	s_waitcnt lgkmcnt(0)
	s_barrier
	s_setprio 1
	s_waitcnt lgkmcnt(0)
	v_mfma_f32_16x16x32_bf16 v[128:131], v[138:141], v[180:183], v[128:131]
	v_mfma_f32_16x16x32_bf16 v[112:115], v[138:141], v[188:191], v[112:115]
	v_mfma_f32_16x16x32_bf16 v[96:99], v[138:141], v[196:199], v[96:99]
	v_mfma_f32_16x16x32_bf16 v[80:83], v[138:141], v[210:213], v[80:83]
	v_mfma_f32_16x16x32_bf16 v[76:79], v[150:153], v[210:213], v[76:79]
	v_mfma_f32_16x16x32_bf16 v[92:95], v[150:153], v[196:199], v[92:95]
	v_mfma_f32_16x16x32_bf16 v[108:111], v[150:153], v[188:191], v[108:111]
	v_mfma_f32_16x16x32_bf16 v[124:127], v[150:153], v[180:183], v[124:127]
	v_mfma_f32_16x16x32_bf16 v[128:131], v[142:145], v[184:187], v[128:131]
	v_mfma_f32_16x16x32_bf16 v[112:115], v[142:145], v[192:195], v[112:115]
	v_mfma_f32_16x16x32_bf16 v[96:99], v[142:145], v[206:209], v[96:99]
	v_mfma_f32_16x16x32_bf16 v[80:83], v[142:145], v[214:217], v[80:83]
	v_mfma_f32_16x16x32_bf16 v[76:79], v[154:157], v[214:217], v[76:79]
	v_mfma_f32_16x16x32_bf16 v[92:95], v[154:157], v[206:209], v[92:95]
	v_mfma_f32_16x16x32_bf16 v[108:111], v[154:157], v[192:195], v[108:111]
	v_mfma_f32_16x16x32_bf16 v[124:127], v[154:157], v[184:187], v[124:127]
	s_setprio 0
	s_setprio 1
	v_mfma_f32_16x16x32_bf16 v[120:123], v[158:161], v[180:183], v[120:123]
	v_mfma_f32_16x16x32_bf16 v[104:107], v[158:161], v[188:191], v[104:107]
	v_mfma_f32_16x16x32_bf16 v[88:91], v[158:161], v[196:199], v[88:91]
	v_mfma_f32_16x16x32_bf16 v[72:75], v[158:161], v[210:213], v[72:75]
	v_mfma_f32_16x16x32_bf16 v[68:71], v[166:169], v[210:213], v[68:71]
	v_mfma_f32_16x16x32_bf16 v[84:87], v[166:169], v[196:199], v[84:87]
	v_mfma_f32_16x16x32_bf16 v[100:103], v[166:169], v[188:191], v[100:103]
	v_mfma_f32_16x16x32_bf16 v[116:119], v[166:169], v[180:183], v[116:119]
	v_mfma_f32_16x16x32_bf16 v[120:123], v[162:165], v[184:187], v[120:123]
	v_mfma_f32_16x16x32_bf16 v[104:107], v[162:165], v[192:195], v[104:107]
	v_mfma_f32_16x16x32_bf16 v[88:91], v[162:165], v[206:209], v[88:91]
	v_mfma_f32_16x16x32_bf16 v[72:75], v[162:165], v[214:217], v[72:75]
	v_mfma_f32_16x16x32_bf16 v[68:71], v[170:173], v[214:217], v[68:71]
	v_mfma_f32_16x16x32_bf16 v[84:87], v[170:173], v[206:209], v[84:87]
	v_mfma_f32_16x16x32_bf16 v[100:103], v[170:173], v[192:195], v[100:103]
	v_mfma_f32_16x16x32_bf16 v[116:119], v[170:173], v[184:187], v[116:119]
	s_setprio 0
	s_barrier
	s_add_i32 s28, s72, s66
	v_lshl_add_u64 v[174:175], v[174:175], 0, s[30:31]
	s_mov_b32 m0, s28
	ds_read_b128 v[180:183], v148 offset:49152
	ds_read_b128 v[184:187], v148 offset:50176
	ds_read_b128 v[188:191], v148 offset:51200
	ds_read_b128 v[192:195], v148 offset:52224
	ds_read_b128 v[196:199], v148 offset:53248
	ds_read_b128 v[206:209], v148 offset:54272
	ds_read_b128 v[210:213], v148 offset:55296
	ds_read_b128 v[214:217], v148 offset:56320
	global_load_lds_dwordx4 v[174:175], off
	s_add_i32 m0, s28, 0x2000
	s_add_u32 s24, s24, 0x100080
	v_lshl_add_u64 v[174:175], v[218:219], 0, s[30:31]
	s_addc_u32 s25, s25, 0
	s_add_i32 s28, s73, s66
	global_load_lds_dwordx4 v[174:175], off
	v_lshl_add_u64 v[174:175], s[24:25], 0, v[132:133]
	s_mov_b32 m0, s28
	s_nop 0
	global_load_lds_dwordx4 v[174:175], off
	v_lshl_add_u64 v[174:175], s[24:25], 0, v[0:1]
	s_add_i32 m0, s28, 0x2000
	s_nop 0
	global_load_lds_dwordx4 v[174:175], off
	v_lshl_add_u64 v[174:175], v[220:221], 0, s[30:31]
	s_mov_b32 m0, s71
	s_nop 0
	global_load_lds_dwordx4 v[174:175], off
	v_lshl_add_u64 v[174:175], v[222:223], 0, s[30:31]
	s_mov_b32 m0, s84
	s_nop 0
	global_load_lds_dwordx4 v[174:175], off
	s_waitcnt vmcnt(8)
	s_waitcnt lgkmcnt(0)
	s_barrier
	s_setprio 1
	s_waitcnt lgkmcnt(0)
	v_mfma_f32_16x16x32_bf16 v[64:67], v[138:141], v[180:183], v[64:67]
	v_mfma_f32_16x16x32_bf16 v[48:51], v[138:141], v[188:191], v[48:51]
	v_mfma_f32_16x16x32_bf16 v[32:35], v[138:141], v[196:199], v[32:35]
	v_mfma_f32_16x16x32_bf16 v[16:19], v[138:141], v[210:213], v[16:19]
	v_mfma_f32_16x16x32_bf16 v[12:15], v[150:153], v[210:213], v[12:15]
	v_mfma_f32_16x16x32_bf16 v[28:31], v[150:153], v[196:199], v[28:31]
	v_mfma_f32_16x16x32_bf16 v[44:47], v[150:153], v[188:191], v[44:47]
	v_mfma_f32_16x16x32_bf16 v[60:63], v[150:153], v[180:183], v[60:63]
	v_mfma_f32_16x16x32_bf16 v[64:67], v[142:145], v[184:187], v[64:67]
	v_mfma_f32_16x16x32_bf16 v[48:51], v[142:145], v[192:195], v[48:51]
	v_mfma_f32_16x16x32_bf16 v[32:35], v[142:145], v[206:209], v[32:35]
	v_mfma_f32_16x16x32_bf16 v[16:19], v[142:145], v[214:217], v[16:19]
	v_mfma_f32_16x16x32_bf16 v[12:15], v[154:157], v[214:217], v[12:15]
	v_mfma_f32_16x16x32_bf16 v[28:31], v[154:157], v[206:209], v[28:31]
	v_mfma_f32_16x16x32_bf16 v[44:47], v[154:157], v[192:195], v[44:47]
	v_mfma_f32_16x16x32_bf16 v[60:63], v[154:157], v[184:187], v[60:63]
	s_setprio 0
	s_setprio 1
	v_mfma_f32_16x16x32_bf16 v[56:59], v[158:161], v[180:183], v[56:59]
	v_mfma_f32_16x16x32_bf16 v[40:43], v[158:161], v[188:191], v[40:43]
	v_mfma_f32_16x16x32_bf16 v[24:27], v[158:161], v[196:199], v[24:27]
	v_mfma_f32_16x16x32_bf16 v[8:11], v[158:161], v[210:213], v[8:11]
	v_mfma_f32_16x16x32_bf16 v[4:7], v[166:169], v[210:213], v[4:7]
	v_mfma_f32_16x16x32_bf16 v[20:23], v[166:169], v[196:199], v[20:23]
	v_mfma_f32_16x16x32_bf16 v[36:39], v[166:169], v[188:191], v[36:39]
	v_mfma_f32_16x16x32_bf16 v[52:55], v[166:169], v[180:183], v[52:55]
	v_mfma_f32_16x16x32_bf16 v[56:59], v[162:165], v[184:187], v[56:59]
	v_mfma_f32_16x16x32_bf16 v[40:43], v[162:165], v[192:195], v[40:43]
	v_mfma_f32_16x16x32_bf16 v[24:27], v[162:165], v[206:209], v[24:27]
	v_mfma_f32_16x16x32_bf16 v[8:11], v[162:165], v[214:217], v[8:11]
	v_mfma_f32_16x16x32_bf16 v[4:7], v[170:173], v[214:217], v[4:7]
	v_mfma_f32_16x16x32_bf16 v[20:23], v[170:173], v[206:209], v[20:23]
	v_mfma_f32_16x16x32_bf16 v[36:39], v[170:173], v[192:195], v[36:39]
	v_mfma_f32_16x16x32_bf16 v[52:55], v[170:173], v[184:187], v[52:55]
	s_setprio 0
	s_barrier
	s_add_i32 s92, s92, 2
	s_add_u32 s90, s90, 0x100
	s_addc_u32 s91, s91, 0
	s_cmp_gt_u32 s92, 61
	s_mov_b64 s[28:29], s[60:61]
	s_cbranch_scc0 .LBB0_961
	s_and_b64 vcc, exec, s[50:51]
	s_cbranch_vccz .LBB0_964
	s_barrier
